# attention epilogue: 64 short stores per lane replaced by per-wave LDS transpose + 8 dwordx4 stores (on top of kv store merge)
# speedup vs baseline: 1.0076x; 1.0018x over previous
; __device__ __forceinline__ int crow(int r,int hi){return (r&3)+8*(r>>2)+4*hi;}
; __device__ __forceinline__ unsigned cvtpk_s(float lo,float hi){f32x2_t v={lo,hi};bf16x2_t b=__builtin_convertvector(v,bf16x2_t);return __builtin_bit_cast(unsigned,b);}
; template<int THRL> __device__ __forceinline__ void attn_unit(int b,int qb,int T0,const bf16*Q,const bf16*__restrict__ K,const bf16*__restrict__ V,float*Dg,float cs,float lam,char*shm){
;     ...
;   if(hi==0)wsf[32+r32]=l_reg;asm volatile("s_waitcnt lgkmcnt(0)":::"memory");
;   float rli[16];
;   #pragma unroll
;   for(int r=0;r<16;++r)rli[r]=__builtin_amdgcn_rcpf(wsf[32+crow(r,hi)]);
;   { typedef __attribute__((address_space(1))) unsigned short gbf16; gbf16*Dw=(gbf16*)Dg+(rowbase+q0+wid*QBLK+4*hi)*768+r32; asm volatile("":"+v"(Dw));
;     #pragma unroll
;     for(int r=0;r<16;++r){
;       #pragma unroll
;       for(int d0=0;d0<4;++d0){ gbf16*p=Dw+((r&3)+8*(r>>2))*768+d0*32; const float v_=o[d0][r]*rli[r]; *p=(unsigned short)cvtpk_s(v_,v_); } } }
.LBB0_304:
	s_or_b64 exec, exec, s[34:35]
	s_waitcnt lgkmcnt(0)
	ds_read_b128 v[2:5], v252 offset:128
	ds_read_b128 v[6:9], v252 offset:160
	ds_read_b128 v[84:87], v252 offset:192
	ds_read_b128 v[88:91], v252 offset:224
	s_add_u32 s22, s96, s52
	s_addc_u32 s23, s97, s53
	s_lshl_b32 s34, s84, 1
	s_add_u32 s22, s22, s34
	s_addc_u32 s23, s23, 0
	v_readfirstlane_b32 s34, v252
	s_lshl_b32 s34, s34, 4
	s_sub_u32 s34, s34, 1103872
	v_lshlrev_b32_e32 v120, 7, v250
	v_lshl_add_u32 v120, v248, 1, v120
	v_add_u32_e32 v120, s34, v120
	v_lshrrev_b32_e32 v122, 3, v240
	v_and_b32_e32 v123, 7, v240
	v_lshlrev_b32_e32 v121, 7, v122
	v_lshl_add_u32 v121, v123, 4, v121
	v_add_u32_e32 v121, s34, v121
	v_or_b32_e32 v122, s79, v122
	v_mov_b64_e32 v[124:125], s[22:23]
	v_mad_i64_i32 v[124:125], s[22:23], v122, s66, v[124:125]
	v_lshlrev_b32_e32 v122, 4, v123
	v_mov_b32_e32 v123, 0
	v_lshl_add_u64 v[124:125], v[124:125], 0, v[122:123]
	s_mov_b64 s[22:23], 0x3000
	v_lshl_add_u64 v[126:127], v[124:125], 0, s[22:23]
	v_lshl_add_u64 v[128:129], v[126:127], 0, s[22:23]
	v_lshl_add_u64 v[130:131], v[128:129], 0, s[22:23]
	s_waitcnt lgkmcnt(0)
	v_rcp_f32_e32 v100, v2
	v_rcp_f32_e32 v101, v3
	v_rcp_f32_e32 v102, v4
	v_rcp_f32_e32 v103, v5
	v_rcp_f32_e32 v104, v6
	v_rcp_f32_e32 v105, v7
	v_rcp_f32_e32 v106, v8
	v_rcp_f32_e32 v107, v9
	v_rcp_f32_e32 v108, v84
	v_rcp_f32_e32 v109, v85
	v_rcp_f32_e32 v110, v86
	v_rcp_f32_e32 v111, v87
	v_rcp_f32_e32 v112, v88
	v_rcp_f32_e32 v113, v89
	v_rcp_f32_e32 v114, v90
	v_rcp_f32_e32 v115, v91
	s_nop 0
	v_mul_f32_e32 v116, v64, v100
	v_mul_f32_e32 v117, v48, v100
	v_cvt_pk_bf16_f32 v116, v116, v117
	ds_write_b16 v120, v116
	ds_write_b16_d16_hi v120, v116 offset:64
	v_mul_f32_e32 v118, v65, v101
	v_mul_f32_e32 v119, v49, v101
	v_cvt_pk_bf16_f32 v118, v118, v119
	ds_write_b16 v120, v118 offset:128
	ds_write_b16_d16_hi v120, v118 offset:192
	v_mul_f32_e32 v116, v66, v102
	v_mul_f32_e32 v117, v50, v102
	v_cvt_pk_bf16_f32 v116, v116, v117
	ds_write_b16 v120, v116 offset:256
	ds_write_b16_d16_hi v120, v116 offset:320
	v_mul_f32_e32 v118, v67, v103
	v_mul_f32_e32 v119, v51, v103
	v_cvt_pk_bf16_f32 v118, v118, v119
	ds_write_b16 v120, v118 offset:384
	ds_write_b16_d16_hi v120, v118 offset:448
	v_mul_f32_e32 v116, v68, v104
	v_mul_f32_e32 v117, v52, v104
	v_cvt_pk_bf16_f32 v116, v116, v117
	ds_write_b16 v120, v116 offset:1024
	ds_write_b16_d16_hi v120, v116 offset:1088
	v_mul_f32_e32 v118, v69, v105
	v_mul_f32_e32 v119, v53, v105
	v_cvt_pk_bf16_f32 v118, v118, v119
	ds_write_b16 v120, v118 offset:1152
	ds_write_b16_d16_hi v120, v118 offset:1216
	v_mul_f32_e32 v116, v70, v106
	v_mul_f32_e32 v117, v54, v106
	v_cvt_pk_bf16_f32 v116, v116, v117
	ds_write_b16 v120, v116 offset:1280
	ds_write_b16_d16_hi v120, v116 offset:1344
	v_mul_f32_e32 v118, v71, v107
	v_mul_f32_e32 v119, v55, v107
	v_cvt_pk_bf16_f32 v118, v118, v119
	ds_write_b16 v120, v118 offset:1408
	ds_write_b16_d16_hi v120, v118 offset:1472
	v_mul_f32_e32 v116, v72, v108
	v_mul_f32_e32 v117, v56, v108
	v_cvt_pk_bf16_f32 v116, v116, v117
	ds_write_b16 v120, v116 offset:2048
	ds_write_b16_d16_hi v120, v116 offset:2112
	v_mul_f32_e32 v118, v73, v109
	v_mul_f32_e32 v119, v57, v109
	v_cvt_pk_bf16_f32 v118, v118, v119
	ds_write_b16 v120, v118 offset:2176
	ds_write_b16_d16_hi v120, v118 offset:2240
	v_mul_f32_e32 v116, v74, v110
	v_mul_f32_e32 v117, v58, v110
	v_cvt_pk_bf16_f32 v116, v116, v117
	ds_write_b16 v120, v116 offset:2304
	ds_write_b16_d16_hi v120, v116 offset:2368
	v_mul_f32_e32 v118, v75, v111
	v_mul_f32_e32 v119, v59, v111
	v_cvt_pk_bf16_f32 v118, v118, v119
	ds_write_b16 v120, v118 offset:2432
	ds_write_b16_d16_hi v120, v118 offset:2496
	v_mul_f32_e32 v116, v76, v112
	v_mul_f32_e32 v117, v60, v112
	v_cvt_pk_bf16_f32 v116, v116, v117
	ds_write_b16 v120, v116 offset:3072
	ds_write_b16_d16_hi v120, v116 offset:3136
	v_mul_f32_e32 v118, v77, v113
	v_mul_f32_e32 v119, v61, v113
	v_cvt_pk_bf16_f32 v118, v118, v119
	ds_write_b16 v120, v118 offset:3200
	ds_write_b16_d16_hi v120, v118 offset:3264
	v_mul_f32_e32 v116, v78, v114
	v_mul_f32_e32 v117, v62, v114
	v_cvt_pk_bf16_f32 v116, v116, v117
	ds_write_b16 v120, v116 offset:3328
	ds_write_b16_d16_hi v120, v116 offset:3392
	v_mul_f32_e32 v118, v79, v115
	v_mul_f32_e32 v119, v63, v115
	v_cvt_pk_bf16_f32 v118, v118, v119
	ds_write_b16 v120, v118 offset:3456
	ds_write_b16_d16_hi v120, v118 offset:3520
	s_waitcnt lgkmcnt(0)
; __device__ __forceinline__ int crow(int r,int hi){return (r&3)+8*(r>>2)+4*hi;}
; __device__ __forceinline__ unsigned cvtpk_s(float lo,float hi){f32x2_t v={lo,hi};bf16x2_t b=__builtin_convertvector(v,bf16x2_t);return __builtin_bit_cast(unsigned,b);}
; template<int THRL> __device__ __forceinline__ void attn_unit(int b,int qb,int T0,const bf16*Q,const bf16*__restrict__ K,const bf16*__restrict__ V,float*Dg,float cs,float lam,char*shm){
;     ...
;   if(hi==0)wsf[32+r32]=l_reg;asm volatile("s_waitcnt lgkmcnt(0)":::"memory");
;   float rli[16];
;   #pragma unroll
;   for(int r=0;r<16;++r)rli[r]=__builtin_amdgcn_rcpf(wsf[32+crow(r,hi)]);
;   { typedef __attribute__((address_space(1))) unsigned short gbf16; gbf16*Dw=(gbf16*)Dg+(rowbase+q0+wid*QBLK+4*hi)*768+r32; asm volatile("":"+v"(Dw));
;     #pragma unroll
;     for(int r=0;r<16;++r){
;       #pragma unroll
;       for(int d0=0;d0<4;++d0){ gbf16*p=Dw+((r&3)+8*(r>>2))*768+d0*32; const float v_=o[d0][r]*rli[r]; *p=(unsigned short)cvtpk_s(v_,v_); } } }
;   asm volatile("s_waitcnt lgkmcnt(0)\n\ts_barrier":::"memory");
	ds_read_b128 v[132:135], v121
	ds_read_b128 v[136:139], v121 offset:1024
	ds_read_b128 v[140:143], v121 offset:2048
	ds_read_b128 v[144:147], v121 offset:3072
	s_waitcnt lgkmcnt(3)
	global_store_dwordx4 v[124:125], v[132:135], off
	s_waitcnt lgkmcnt(2)
	global_store_dwordx4 v[126:127], v[136:139], off
	s_waitcnt lgkmcnt(1)
	global_store_dwordx4 v[128:129], v[140:143], off
	s_waitcnt lgkmcnt(0)
	global_store_dwordx4 v[130:131], v[144:147], off
	v_mul_f32_e32 v116, v32, v100
	v_mul_f32_e32 v117, v16, v100
	v_cvt_pk_bf16_f32 v116, v116, v117
	ds_write_b16 v120, v116
	ds_write_b16_d16_hi v120, v116 offset:64
	v_mul_f32_e32 v118, v33, v101
	v_mul_f32_e32 v119, v17, v101
	v_cvt_pk_bf16_f32 v118, v118, v119
	ds_write_b16 v120, v118 offset:128
	ds_write_b16_d16_hi v120, v118 offset:192
	v_mul_f32_e32 v116, v34, v102
	v_mul_f32_e32 v117, v18, v102
	v_cvt_pk_bf16_f32 v116, v116, v117
	ds_write_b16 v120, v116 offset:256
	ds_write_b16_d16_hi v120, v116 offset:320
	v_mul_f32_e32 v118, v35, v103
	v_mul_f32_e32 v119, v19, v103
	v_cvt_pk_bf16_f32 v118, v118, v119
	ds_write_b16 v120, v118 offset:384
	ds_write_b16_d16_hi v120, v118 offset:448
	v_mul_f32_e32 v116, v36, v104
	v_mul_f32_e32 v117, v20, v104
	v_cvt_pk_bf16_f32 v116, v116, v117
	ds_write_b16 v120, v116 offset:1024
	ds_write_b16_d16_hi v120, v116 offset:1088
	v_mul_f32_e32 v118, v37, v105
	v_mul_f32_e32 v119, v21, v105
	v_cvt_pk_bf16_f32 v118, v118, v119
	ds_write_b16 v120, v118 offset:1152
	ds_write_b16_d16_hi v120, v118 offset:1216
	v_mul_f32_e32 v116, v38, v106
	v_mul_f32_e32 v117, v22, v106
	v_cvt_pk_bf16_f32 v116, v116, v117
	ds_write_b16 v120, v116 offset:1280
	ds_write_b16_d16_hi v120, v116 offset:1344
	v_mul_f32_e32 v118, v39, v107
	v_mul_f32_e32 v119, v23, v107
	v_cvt_pk_bf16_f32 v118, v118, v119
	ds_write_b16 v120, v118 offset:1408
	ds_write_b16_d16_hi v120, v118 offset:1472
	v_mul_f32_e32 v116, v40, v108
	v_mul_f32_e32 v117, v24, v108
	v_cvt_pk_bf16_f32 v116, v116, v117
	ds_write_b16 v120, v116 offset:2048
	ds_write_b16_d16_hi v120, v116 offset:2112
	v_mul_f32_e32 v118, v41, v109
	v_mul_f32_e32 v119, v25, v109
	v_cvt_pk_bf16_f32 v118, v118, v119
	ds_write_b16 v120, v118 offset:2176
	ds_write_b16_d16_hi v120, v118 offset:2240
	v_mul_f32_e32 v116, v42, v110
	v_mul_f32_e32 v117, v26, v110
	v_cvt_pk_bf16_f32 v116, v116, v117
	ds_write_b16 v120, v116 offset:2304
	ds_write_b16_d16_hi v120, v116 offset:2368
	v_mul_f32_e32 v118, v43, v111
	v_mul_f32_e32 v119, v27, v111
	v_cvt_pk_bf16_f32 v118, v118, v119
	ds_write_b16 v120, v118 offset:2432
	ds_write_b16_d16_hi v120, v118 offset:2496
	v_mul_f32_e32 v116, v44, v112
	v_mul_f32_e32 v117, v28, v112
	v_cvt_pk_bf16_f32 v116, v116, v117
	ds_write_b16 v120, v116 offset:3072
	ds_write_b16_d16_hi v120, v116 offset:3136
	v_mul_f32_e32 v118, v45, v113
	v_mul_f32_e32 v119, v29, v113
	v_cvt_pk_bf16_f32 v118, v118, v119
	ds_write_b16 v120, v118 offset:3200
	ds_write_b16_d16_hi v120, v118 offset:3264
	v_mul_f32_e32 v116, v46, v114
	v_mul_f32_e32 v117, v30, v114
	v_cvt_pk_bf16_f32 v116, v116, v117
	ds_write_b16 v120, v116 offset:3328
	ds_write_b16_d16_hi v120, v116 offset:3392
	v_mul_f32_e32 v118, v47, v115
	v_mul_f32_e32 v119, v31, v115
	v_cvt_pk_bf16_f32 v118, v118, v119
	ds_write_b16 v120, v118 offset:3456
	ds_write_b16_d16_hi v120, v118 offset:3520
	s_waitcnt lgkmcnt(0)
	ds_read_b128 v[132:135], v121
	ds_read_b128 v[136:139], v121 offset:1024
	ds_read_b128 v[140:143], v121 offset:2048
	ds_read_b128 v[144:147], v121 offset:3072
	s_waitcnt lgkmcnt(3)
	global_store_dwordx4 v[124:125], v[132:135], off offset:128
	s_waitcnt lgkmcnt(2)
	global_store_dwordx4 v[126:127], v[136:139], off offset:128
	s_waitcnt lgkmcnt(1)
	global_store_dwordx4 v[128:129], v[140:143], off offset:128
	s_waitcnt lgkmcnt(0)
	global_store_dwordx4 v[130:131], v[144:147], off offset:128
	s_waitcnt lgkmcnt(0)
	s_barrier
	s_mov_b64 s[44:45], 0
